# sec 7.11 loop-edge edit: P4/P9 GEMM K-loop counter/exit test moved in front of the loop-back barrier
# baseline (speedup 1.0000x reference)
.LBB0_850:
	s_add_u32 s62, s42, 0xfffc0080
	s_addc_u32 s63, s43, -1
	s_add_i32 s67, 0, 0x10000
	s_cmp_eq_u32 s19, 12
	s_cselect_b32 s89, s30, s63
	s_cselect_b32 s88, s31, s62
	v_add_u32_e32 v140, s67, v147
	s_cselect_b32 s85, s49, s35
	s_cselect_b32 s84, s61, s34
	s_add_i32 s62, 0, 0x14000
	ds_read_b128 v[154:157], v140
	ds_read_b128 v[158:161], v140 offset:1024
	ds_read_b128 v[162:165], v140 offset:2048
	ds_read_b128 v[166:169], v140 offset:3072
	v_add_u32_e32 v140, s62, v147
	ds_read_b128 v[170:173], v140
	ds_read_b128 v[186:189], v140 offset:1024
	ds_read_b128 v[190:193], v140 offset:2048
	ds_read_b128 v[194:197], v140 offset:3072
	v_lshl_add_u64 v[140:141], s[42:43], 0, v[136:137]
	s_add_i32 m0, s23, 0xc000
	ds_read_b128 v[198:201], v153
	ds_read_b128 v[212:215], v153 offset:1024
	ds_read_b128 v[226:229], v153 offset:2048
	ds_read_b128 v[230:233], v153 offset:3072
	ds_read_b128 v[234:237], v153 offset:4096
	ds_read_b128 v[240:243], v153 offset:5120
	ds_read_b128 v[244:247], v153 offset:6144
	ds_read_b128 v[248:251], v153 offset:7168
	global_load_lds_dwordx4 v[140:141], off
	v_lshl_add_u64 v[140:141], s[42:43], 0, v[138:139]
	s_add_i32 m0, s23, 0xe000
	s_nop 0
	global_load_lds_dwordx4 v[140:141], off
	s_waitcnt vmcnt(8)
	s_waitcnt lgkmcnt(0)
	s_barrier
	s_setprio 1
	s_waitcnt lgkmcnt(0)
	v_mfma_f32_16x16x32_bf16 v[126:129], v[154:157], v[198:201], v[126:129]
	v_mfma_f32_16x16x32_bf16 v[122:125], v[162:165], v[198:201], v[122:125]
	v_mfma_f32_16x16x32_bf16 v[110:113], v[154:157], v[226:229], v[110:113]
	v_mfma_f32_16x16x32_bf16 v[106:109], v[162:165], v[226:229], v[106:109]
	v_mfma_f32_16x16x32_bf16 v[94:97], v[154:157], v[234:237], v[94:97]
	v_mfma_f32_16x16x32_bf16 v[90:93], v[162:165], v[234:237], v[90:93]
	v_mfma_f32_16x16x32_bf16 v[78:81], v[154:157], v[244:247], v[78:81]
	v_mfma_f32_16x16x32_bf16 v[74:77], v[162:165], v[244:247], v[74:77]
	v_mfma_f32_16x16x32_bf16 v[126:129], v[158:161], v[212:215], v[126:129]
	v_mfma_f32_16x16x32_bf16 v[122:125], v[166:169], v[212:215], v[122:125]
	v_mfma_f32_16x16x32_bf16 v[110:113], v[158:161], v[230:233], v[110:113]
	v_mfma_f32_16x16x32_bf16 v[106:109], v[166:169], v[230:233], v[106:109]
	v_mfma_f32_16x16x32_bf16 v[94:97], v[158:161], v[240:243], v[94:97]
	v_mfma_f32_16x16x32_bf16 v[90:93], v[166:169], v[240:243], v[90:93]
	v_mfma_f32_16x16x32_bf16 v[78:81], v[158:161], v[248:251], v[78:81]
	v_mfma_f32_16x16x32_bf16 v[74:77], v[166:169], v[248:251], v[74:77]
	s_setprio 0
	s_setprio 1
	v_mfma_f32_16x16x32_bf16 v[118:121], v[170:173], v[198:201], v[118:121]
	v_mfma_f32_16x16x32_bf16 v[114:117], v[190:193], v[198:201], v[114:117]
	v_mfma_f32_16x16x32_bf16 v[102:105], v[170:173], v[226:229], v[102:105]
	v_mfma_f32_16x16x32_bf16 v[98:101], v[190:193], v[226:229], v[98:101]
	v_mfma_f32_16x16x32_bf16 v[86:89], v[170:173], v[234:237], v[86:89]
	v_mfma_f32_16x16x32_bf16 v[82:85], v[190:193], v[234:237], v[82:85]
	v_mfma_f32_16x16x32_bf16 v[70:73], v[170:173], v[244:247], v[70:73]
	v_mfma_f32_16x16x32_bf16 v[66:69], v[190:193], v[244:247], v[66:69]
	v_mfma_f32_16x16x32_bf16 v[118:121], v[186:189], v[212:215], v[118:121]
	v_mfma_f32_16x16x32_bf16 v[114:117], v[194:197], v[212:215], v[114:117]
	v_mfma_f32_16x16x32_bf16 v[102:105], v[186:189], v[230:233], v[102:105]
	v_mfma_f32_16x16x32_bf16 v[98:101], v[194:197], v[230:233], v[98:101]
	v_mfma_f32_16x16x32_bf16 v[86:89], v[186:189], v[240:243], v[86:89]
	v_mfma_f32_16x16x32_bf16 v[82:85], v[194:197], v[240:243], v[82:85]
	v_mfma_f32_16x16x32_bf16 v[70:73], v[186:189], v[248:251], v[70:73]
	v_mfma_f32_16x16x32_bf16 v[66:69], v[194:197], v[248:251], v[66:69]
	s_setprio 0
	s_barrier
	s_add_i32 s63, s67, s22
	v_lshl_add_u64 v[140:141], s[84:85], 0, v[0:1]
	s_mov_b32 m0, s63
	ds_read_b128 v[198:201], v153 offset:16384
	ds_read_b128 v[212:215], v153 offset:17408
	ds_read_b128 v[226:229], v153 offset:18432
	ds_read_b128 v[230:233], v153 offset:19456
	ds_read_b128 v[234:237], v153 offset:20480
	ds_read_b128 v[240:243], v153 offset:21504
	ds_read_b128 v[244:247], v153 offset:22528
	ds_read_b128 v[248:251], v153 offset:23552
	global_load_lds_dwordx4 v[140:141], off
	s_add_i32 m0, s63, 0x2000
	s_add_u32 s92, s84, 0x40000
	v_lshl_add_u64 v[144:145], s[84:85], 0, v[130:131]
	s_addc_u32 s93, s85, 0
	s_add_i32 s62, s62, s22
	global_load_lds_dwordx4 v[144:145], off
	v_lshl_add_u64 v[174:175], s[92:93], 0, v[0:1]
	s_mov_b32 m0, s62
	v_lshl_add_u64 v[202:203], s[88:89], 0, v[132:133]
	global_load_lds_dwordx4 v[174:175], off
	v_lshl_add_u64 v[174:175], s[92:93], 0, v[130:131]
	s_add_i32 m0, s62, 0x2000
	s_nop 0
	global_load_lds_dwordx4 v[174:175], off
	v_lshl_add_u64 v[174:175], s[88:89], 0, v[134:135]
	s_mov_b32 m0, s23
	s_nop 0
	global_load_lds_dwordx4 v[174:175], off
	s_mov_b32 m0, s24
	s_nop 0
	global_load_lds_dwordx4 v[202:203], off
	s_waitcnt vmcnt(8)
	s_waitcnt lgkmcnt(0)
	s_barrier
	s_setprio 1
	s_waitcnt lgkmcnt(0)
	v_mfma_f32_16x16x32_bf16 v[62:65], v[154:157], v[198:201], v[62:65]
	v_mfma_f32_16x16x32_bf16 v[58:61], v[162:165], v[198:201], v[58:61]
	v_mfma_f32_16x16x32_bf16 v[46:49], v[154:157], v[226:229], v[46:49]
	v_mfma_f32_16x16x32_bf16 v[42:45], v[162:165], v[226:229], v[42:45]
	v_mfma_f32_16x16x32_bf16 v[30:33], v[154:157], v[234:237], v[30:33]
	v_mfma_f32_16x16x32_bf16 v[26:29], v[162:165], v[234:237], v[26:29]
	v_mfma_f32_16x16x32_bf16 v[14:17], v[154:157], v[244:247], v[14:17]
	v_mfma_f32_16x16x32_bf16 v[10:13], v[162:165], v[244:247], v[10:13]
	v_mfma_f32_16x16x32_bf16 v[62:65], v[158:161], v[212:215], v[62:65]
	v_mfma_f32_16x16x32_bf16 v[58:61], v[166:169], v[212:215], v[58:61]
	v_mfma_f32_16x16x32_bf16 v[46:49], v[158:161], v[230:233], v[46:49]
	v_mfma_f32_16x16x32_bf16 v[42:45], v[166:169], v[230:233], v[42:45]
	v_mfma_f32_16x16x32_bf16 v[30:33], v[158:161], v[240:243], v[30:33]
	v_mfma_f32_16x16x32_bf16 v[26:29], v[166:169], v[240:243], v[26:29]
	v_mfma_f32_16x16x32_bf16 v[14:17], v[158:161], v[248:251], v[14:17]
	v_mfma_f32_16x16x32_bf16 v[10:13], v[166:169], v[248:251], v[10:13]
	s_setprio 0
	s_setprio 1
	v_mfma_f32_16x16x32_bf16 v[54:57], v[170:173], v[198:201], v[54:57]
	v_mfma_f32_16x16x32_bf16 v[50:53], v[190:193], v[198:201], v[50:53]
	v_mfma_f32_16x16x32_bf16 v[38:41], v[170:173], v[226:229], v[38:41]
	v_mfma_f32_16x16x32_bf16 v[34:37], v[190:193], v[226:229], v[34:37]
	v_mfma_f32_16x16x32_bf16 v[22:25], v[170:173], v[234:237], v[22:25]
	v_mfma_f32_16x16x32_bf16 v[18:21], v[190:193], v[234:237], v[18:21]
	v_mfma_f32_16x16x32_bf16 v[6:9], v[170:173], v[244:247], v[6:9]
	v_mfma_f32_16x16x32_bf16 v[2:5], v[190:193], v[244:247], v[2:5]
	v_mfma_f32_16x16x32_bf16 v[54:57], v[186:189], v[212:215], v[54:57]
	v_mfma_f32_16x16x32_bf16 v[50:53], v[194:197], v[212:215], v[50:53]
	v_mfma_f32_16x16x32_bf16 v[38:41], v[186:189], v[230:233], v[38:41]
	v_mfma_f32_16x16x32_bf16 v[34:37], v[194:197], v[230:233], v[34:37]
	v_mfma_f32_16x16x32_bf16 v[22:25], v[186:189], v[240:243], v[22:25]
	v_mfma_f32_16x16x32_bf16 v[18:21], v[194:197], v[240:243], v[18:21]
	v_mfma_f32_16x16x32_bf16 v[6:9], v[186:189], v[248:251], v[6:9]
	v_mfma_f32_16x16x32_bf16 v[2:5], v[194:197], v[248:251], v[2:5]
	s_setprio 0
	s_barrier
	s_add_i32 s62, 0, 0x18000
	v_add_u32_e32 v142, s62, v147
	s_add_i32 s63, 0, 0x1c000
	ds_read_b128 v[154:157], v142
	ds_read_b128 v[158:161], v142 offset:1024
	ds_read_b128 v[162:165], v142 offset:2048
	ds_read_b128 v[166:169], v142 offset:3072
	v_add_u32_e32 v142, s63, v147
	ds_read_b128 v[170:173], v142
	ds_read_b128 v[186:189], v142 offset:1024
	ds_read_b128 v[190:193], v142 offset:2048
	ds_read_b128 v[194:197], v142 offset:3072
	s_add_u32 s88, s88, 0x40000
	s_addc_u32 s89, s89, 0
	s_mov_b32 m0, s25
	v_lshl_add_u64 v[222:223], s[88:89], 0, v[134:135]
	ds_read_b128 v[198:201], v153 offset:32768
	ds_read_b128 v[212:215], v153 offset:33792
	ds_read_b128 v[226:229], v153 offset:34816
	ds_read_b128 v[230:233], v153 offset:35840
	ds_read_b128 v[234:237], v153 offset:36864
	ds_read_b128 v[240:243], v153 offset:37888
	ds_read_b128 v[244:247], v153 offset:38912
	ds_read_b128 v[248:251], v153 offset:39936
	global_load_lds_dwordx4 v[222:223], off
	v_lshl_add_u64 v[222:223], s[88:89], 0, v[132:133]
	s_mov_b32 m0, s26
	s_nop 0
	global_load_lds_dwordx4 v[222:223], off
	s_waitcnt vmcnt(8)
	s_waitcnt lgkmcnt(0)
	s_barrier
	s_setprio 1
	s_waitcnt lgkmcnt(0)
	v_mfma_f32_16x16x32_bf16 v[126:129], v[154:157], v[198:201], v[126:129]
	v_mfma_f32_16x16x32_bf16 v[122:125], v[162:165], v[198:201], v[122:125]
	v_mfma_f32_16x16x32_bf16 v[110:113], v[154:157], v[226:229], v[110:113]
	v_mfma_f32_16x16x32_bf16 v[106:109], v[162:165], v[226:229], v[106:109]
	v_mfma_f32_16x16x32_bf16 v[94:97], v[154:157], v[234:237], v[94:97]
	v_mfma_f32_16x16x32_bf16 v[90:93], v[162:165], v[234:237], v[90:93]
	v_mfma_f32_16x16x32_bf16 v[78:81], v[154:157], v[244:247], v[78:81]
	v_mfma_f32_16x16x32_bf16 v[74:77], v[162:165], v[244:247], v[74:77]
	v_mfma_f32_16x16x32_bf16 v[126:129], v[158:161], v[212:215], v[126:129]
	v_mfma_f32_16x16x32_bf16 v[122:125], v[166:169], v[212:215], v[122:125]
	v_mfma_f32_16x16x32_bf16 v[110:113], v[158:161], v[230:233], v[110:113]
	v_mfma_f32_16x16x32_bf16 v[106:109], v[166:169], v[230:233], v[106:109]
	v_mfma_f32_16x16x32_bf16 v[94:97], v[158:161], v[240:243], v[94:97]
	v_mfma_f32_16x16x32_bf16 v[90:93], v[166:169], v[240:243], v[90:93]
	v_mfma_f32_16x16x32_bf16 v[78:81], v[158:161], v[248:251], v[78:81]
	v_mfma_f32_16x16x32_bf16 v[74:77], v[166:169], v[248:251], v[74:77]
	s_setprio 0
	s_setprio 1
	v_mfma_f32_16x16x32_bf16 v[118:121], v[170:173], v[198:201], v[118:121]
	v_mfma_f32_16x16x32_bf16 v[114:117], v[190:193], v[198:201], v[114:117]
	v_mfma_f32_16x16x32_bf16 v[102:105], v[170:173], v[226:229], v[102:105]
	v_mfma_f32_16x16x32_bf16 v[98:101], v[190:193], v[226:229], v[98:101]
	v_mfma_f32_16x16x32_bf16 v[86:89], v[170:173], v[234:237], v[86:89]
	v_mfma_f32_16x16x32_bf16 v[82:85], v[190:193], v[234:237], v[82:85]
	v_mfma_f32_16x16x32_bf16 v[70:73], v[170:173], v[244:247], v[70:73]
	v_mfma_f32_16x16x32_bf16 v[66:69], v[190:193], v[244:247], v[66:69]
	v_mfma_f32_16x16x32_bf16 v[118:121], v[186:189], v[212:215], v[118:121]
	v_mfma_f32_16x16x32_bf16 v[114:117], v[194:197], v[212:215], v[114:117]
	v_mfma_f32_16x16x32_bf16 v[102:105], v[186:189], v[230:233], v[102:105]
	v_mfma_f32_16x16x32_bf16 v[98:101], v[194:197], v[230:233], v[98:101]
	v_mfma_f32_16x16x32_bf16 v[86:89], v[186:189], v[240:243], v[86:89]
	v_mfma_f32_16x16x32_bf16 v[82:85], v[194:197], v[240:243], v[82:85]
	v_mfma_f32_16x16x32_bf16 v[70:73], v[186:189], v[248:251], v[70:73]
	v_mfma_f32_16x16x32_bf16 v[66:69], v[194:197], v[248:251], v[66:69]
	s_setprio 0
	s_barrier
	s_add_i32 s62, s62, s22
	v_lshl_add_u64 v[140:141], v[140:141], 0, s[90:91]
	s_mov_b32 m0, s62
	ds_read_b128 v[198:201], v153 offset:49152
	ds_read_b128 v[212:215], v153 offset:50176
	ds_read_b128 v[226:229], v153 offset:51200
	ds_read_b128 v[230:233], v153 offset:52224
	ds_read_b128 v[234:237], v153 offset:53248
	ds_read_b128 v[240:243], v153 offset:54272
	ds_read_b128 v[244:247], v153 offset:55296
	ds_read_b128 v[248:251], v153 offset:56320
	global_load_lds_dwordx4 v[140:141], off
	s_add_i32 m0, s62, 0x2000
	s_add_u32 s84, s84, 0x40080
	v_lshl_add_u64 v[140:141], v[144:145], 0, s[90:91]
	s_addc_u32 s85, s85, 0
	s_add_i32 s62, s63, s22
	global_load_lds_dwordx4 v[140:141], off
	v_lshl_add_u64 v[140:141], s[84:85], 0, v[0:1]
	s_mov_b32 m0, s62
	s_nop 0
	global_load_lds_dwordx4 v[140:141], off
	v_lshl_add_u64 v[140:141], s[84:85], 0, v[130:131]
	s_add_i32 m0, s62, 0x2000
	s_nop 0
	global_load_lds_dwordx4 v[140:141], off
	v_lshl_add_u64 v[140:141], v[174:175], 0, s[90:91]
	s_mov_b32 m0, s27
	s_nop 0
	global_load_lds_dwordx4 v[140:141], off
	v_lshl_add_u64 v[140:141], v[202:203], 0, s[90:91]
	s_mov_b32 m0, s28
	s_nop 0
	global_load_lds_dwordx4 v[140:141], off
	s_waitcnt vmcnt(8)
	s_waitcnt lgkmcnt(0)
	s_barrier
	s_setprio 1
	s_waitcnt lgkmcnt(0)
	v_mfma_f32_16x16x32_bf16 v[62:65], v[154:157], v[198:201], v[62:65]
	v_mfma_f32_16x16x32_bf16 v[58:61], v[162:165], v[198:201], v[58:61]
	v_mfma_f32_16x16x32_bf16 v[46:49], v[154:157], v[226:229], v[46:49]
	v_mfma_f32_16x16x32_bf16 v[42:45], v[162:165], v[226:229], v[42:45]
	v_mfma_f32_16x16x32_bf16 v[30:33], v[154:157], v[234:237], v[30:33]
	v_mfma_f32_16x16x32_bf16 v[26:29], v[162:165], v[234:237], v[26:29]
	v_mfma_f32_16x16x32_bf16 v[14:17], v[154:157], v[244:247], v[14:17]
	v_mfma_f32_16x16x32_bf16 v[10:13], v[162:165], v[244:247], v[10:13]
	v_mfma_f32_16x16x32_bf16 v[62:65], v[158:161], v[212:215], v[62:65]
	v_mfma_f32_16x16x32_bf16 v[58:61], v[166:169], v[212:215], v[58:61]
	v_mfma_f32_16x16x32_bf16 v[46:49], v[158:161], v[230:233], v[46:49]
	v_mfma_f32_16x16x32_bf16 v[42:45], v[166:169], v[230:233], v[42:45]
	v_mfma_f32_16x16x32_bf16 v[30:33], v[158:161], v[240:243], v[30:33]
	v_mfma_f32_16x16x32_bf16 v[26:29], v[166:169], v[240:243], v[26:29]
	v_mfma_f32_16x16x32_bf16 v[14:17], v[158:161], v[248:251], v[14:17]
	v_mfma_f32_16x16x32_bf16 v[10:13], v[166:169], v[248:251], v[10:13]
	s_setprio 0
	s_setprio 1
	v_mfma_f32_16x16x32_bf16 v[54:57], v[170:173], v[198:201], v[54:57]
	v_mfma_f32_16x16x32_bf16 v[50:53], v[190:193], v[198:201], v[50:53]
	v_mfma_f32_16x16x32_bf16 v[38:41], v[170:173], v[226:229], v[38:41]
	v_mfma_f32_16x16x32_bf16 v[34:37], v[190:193], v[226:229], v[34:37]
	v_mfma_f32_16x16x32_bf16 v[22:25], v[170:173], v[234:237], v[22:25]
	v_mfma_f32_16x16x32_bf16 v[18:21], v[190:193], v[234:237], v[18:21]
	v_mfma_f32_16x16x32_bf16 v[6:9], v[170:173], v[244:247], v[6:9]
	v_mfma_f32_16x16x32_bf16 v[2:5], v[190:193], v[244:247], v[2:5]
	v_mfma_f32_16x16x32_bf16 v[54:57], v[186:189], v[212:215], v[54:57]
	v_mfma_f32_16x16x32_bf16 v[50:53], v[194:197], v[212:215], v[50:53]
	v_mfma_f32_16x16x32_bf16 v[38:41], v[186:189], v[230:233], v[38:41]
	v_mfma_f32_16x16x32_bf16 v[34:37], v[194:197], v[230:233], v[34:37]
	v_mfma_f32_16x16x32_bf16 v[22:25], v[186:189], v[240:243], v[22:25]
	v_mfma_f32_16x16x32_bf16 v[18:21], v[194:197], v[240:243], v[18:21]
	v_mfma_f32_16x16x32_bf16 v[6:9], v[186:189], v[248:251], v[6:9]
	v_mfma_f32_16x16x32_bf16 v[2:5], v[194:197], v[248:251], v[2:5]
	s_setprio 0
	s_add_i32 s19, s19, 2
	s_add_u32 s42, s42, 0x100
	s_addc_u32 s43, s43, 0
	s_add_u32 s34, s34, 0x100
	s_addc_u32 s35, s35, 0
	s_cmp_gt_u32 s19, 13
	s_barrier
	s_cbranch_scc0 .LBB0_850
	s_and_b64 vcc, exec, s[44:45]
	s_cbranch_vccz .LBB0_853
	s_barrier
